# x15 + prologue weight conversion: after an item's loads land, one load touches the 64 rows of the wave's next item so its 32 loads hit L2 (software prefetch)
# speedup vs baseline: 1.0344x; 1.0010x over previous
.LBB0_469:
	s_cselect_b32 s32, 1, 0
	s_add_i32 s88, s30, s0
	s_cmp_gt_i32 s88, 0x103ff
	s_cbranch_scc1 .Ltp_end_in
	s_cmp_ge_u32 s88, 0x8200
	s_cselect_b32 s92, 1, 0
	s_cselect_b32 s81, 0x8200, 0
	s_sub_i32 s88, s88, s81
	s_cmp_lt_u32 s88, 0x3000
	s_cbranch_scc0 .Ltp_b_in
	s_mul_i32 s81, s92, 0x6000000
	s_add_u32 s84, s60, s81
	s_addc_u32 s85, s61, 0
	s_lshr_b32 s81, s88, 7
	s_mul_i32 s81, s81, 0xaaab
	s_lshr_b32 s81, s81, 17
	s_mul_i32 s90, s81, 0x180
	s_sub_i32 s88, s88, s90
	s_mov_b32 s90, 0xc000
	s_branch .Ltp_go_in
.Ltp_b_in:
	s_sub_i32 s88, s88, 0x3000
	s_cmp_lt_u32 s88, 0x800
	s_cbranch_scc0 .Ltp_c_in
	s_lshl_b32 s81, s92, 24
	s_add_u32 s84, s66, s81
	s_addc_u32 s85, s67, 0
	s_lshr_b32 s81, s88, 6
	s_and_b32 s88, s88, 63
	s_movk_i32 s90, 0x2000
	s_branch .Ltp_go_in
.Ltp_c_in:
	s_sub_i32 s88, s88, 0x800
	s_cmp_lt_u32 s88, 0x800
	s_cbranch_scc0 .Ltp_d_in
	s_lshl_b32 s81, s92, 24
	s_add_u32 s84, s68, s81
	s_addc_u32 s85, s69, 0
	s_lshr_b32 s81, s88, 6
	s_and_b32 s88, s88, 63
	s_movk_i32 s90, 0x2000
	s_branch .Ltp_go_in
.Ltp_d_in:
	s_sub_i32 s88, s88, 0x800
	s_cmp_lt_u32 s88, 0x2c00
	s_cbranch_scc0 .Ltp_e_in
	s_mul_i32 s81, s92, 0x5800000
	v_readlane_b32 s84, v254, 45
	v_readlane_b32 s85, v254, 46
	s_nop 1
	s_add_u32 s84, s84, s81
	s_addc_u32 s85, s85, 0
	s_lshr_b32 s81, s88, 5
	s_mul_i32 s81, s81, 0x1746
	s_lshr_b32 s81, s81, 16
	s_mul_i32 s90, s81, 0x160
	s_sub_i32 s88, s88, s90
	s_mov_b32 s90, 0xb000
	s_branch .Ltp_go_in
.Ltp_e_in:
	s_sub_i32 s88, s88, 0x2c00
	s_mul_i32 s81, s92, 0x2c00000
	v_readlane_b32 s84, v254, 47
	v_readlane_b32 s85, v254, 48
	s_nop 1
	s_add_u32 s84, s84, s81
	s_addc_u32 s85, s85, 0
	s_lshr_b32 s81, s88, 6
	s_and_b32 s88, s88, 63
	s_movk_i32 s90, 0x2000
.Ltp_go_in:
	s_lshl_b32 s88, s88, 7
	s_add_u32 s84, s84, s88
	s_addc_u32 s85, s85, 0
	s_lshl_b32 s81, s81, 6
	v_add_u32_e32 v134, s81, v240
	v_mul_u32_u24_e32 v134, s90, v134
	global_load_dword v135, v134, s[84:85]
.Ltp_end_in:
	s_cmp_lg_u32 s32, 0
	ds_write_b32 v64, v63 offset:4488
	s_mul_i32 s7, s14, 0x3000000
	s_waitcnt lgkmcnt(0)
	s_mul_hi_i32 s6, s14, 0x3000000
	s_add_u32 s14, s26, s7
	ds_read2_b32 v[6:7], v73 offset0:33 offset1:41
	ds_read2_b32 v[8:9], v73 offset1:8
	ds_read2_b32 v[10:11], v73 offset0:66 offset1:74
	ds_read2_b32 v[12:13], v73 offset0:99 offset1:107
	ds_read2_b32 v[14:15], v73 offset0:132 offset1:140
	ds_read2_b32 v[16:17], v73 offset0:165 offset1:173
	ds_read2_b32 v[18:19], v73 offset0:198 offset1:206
	ds_read2_b32 v[20:21], v73 offset0:231 offset1:239
	s_addc_u32 s15, s27, s6
	s_lshl_b64 s[6:7], s[18:19], 1
	s_add_u32 s6, s14, s6
	v_or_b32_e32 v22, s16, v72
	s_addc_u32 s7, s15, s7
	v_lshlrev_b32_e32 v64, 1, v70
	v_ashrrev_i32_e32 v23, 31, v22
	v_lshl_add_u64 v[4:5], s[6:7], 0, v[64:65]
	v_lshlrev_b64 v[22:23], 12, v[22:23]
	s_waitcnt lgkmcnt(6)
	v_cvt_pk_bf16_f32 v0, v8, v6
	s_waitcnt lgkmcnt(4)
	v_cvt_pk_bf16_f32 v1, v10, v12
	s_waitcnt lgkmcnt(2)
	v_cvt_pk_bf16_f32 v2, v14, v16
	s_waitcnt lgkmcnt(0)
	v_cvt_pk_bf16_f32 v3, v18, v20
	v_lshl_add_u64 v[22:23], v[4:5], 0, v[22:23]
	v_or_b32_e32 v6, s16, v74
	global_store_dwordx4 v[22:23], v[0:3], off
	v_or_b32_e32 v22, s16, v75
	v_ashrrev_i32_e32 v23, 31, v22
	v_cvt_pk_bf16_f32 v0, v9, v7
	v_ashrrev_i32_e32 v7, 31, v6
	v_lshlrev_b64 v[6:7], 12, v[6:7]
	v_cvt_pk_bf16_f32 v1, v11, v13
	v_cvt_pk_bf16_f32 v2, v15, v17
	v_cvt_pk_bf16_f32 v3, v19, v21
	v_lshl_add_u64 v[6:7], v[4:5], 0, v[6:7]
	global_store_dwordx4 v[6:7], v[0:3], off
	ds_read2_b32 v[6:7], v73 offset0:49 offset1:57
	ds_read2_b32 v[8:9], v73 offset0:16 offset1:24
	ds_read2_b32 v[10:11], v73 offset0:82 offset1:90
	ds_read2_b32 v[12:13], v73 offset0:115 offset1:123
	ds_read2_b32 v[14:15], v73 offset0:148 offset1:156
	ds_read2_b32 v[16:17], v73 offset0:181 offset1:189
	ds_read2_b32 v[18:19], v73 offset0:214 offset1:222
	ds_read2_b32 v[20:21], v73 offset0:247 offset1:255
	v_lshlrev_b64 v[22:23], 12, v[22:23]
	s_waitcnt lgkmcnt(6)
	v_cvt_pk_bf16_f32 v0, v8, v6
	s_waitcnt lgkmcnt(4)
	v_cvt_pk_bf16_f32 v1, v10, v12
	s_waitcnt lgkmcnt(2)
	v_cvt_pk_bf16_f32 v2, v14, v16
	s_waitcnt lgkmcnt(0)
	v_cvt_pk_bf16_f32 v3, v18, v20
	v_lshl_add_u64 v[22:23], v[4:5], 0, v[22:23]
	v_or_b32_e32 v6, s16, v76
	global_store_dwordx4 v[22:23], v[0:3], off
	s_nop 1
	v_cvt_pk_bf16_f32 v0, v9, v7
	v_ashrrev_i32_e32 v7, 31, v6
	v_lshlrev_b64 v[6:7], 12, v[6:7]
	v_cvt_pk_bf16_f32 v1, v11, v13
	v_cvt_pk_bf16_f32 v2, v15, v17
	v_cvt_pk_bf16_f32 v3, v19, v21
	v_lshl_add_u64 v[4:5], v[4:5], 0, v[6:7]
	global_store_dwordx4 v[4:5], v[0:3], off
	s_waitcnt lgkmcnt(0)

.LBB0_471:
	s_mul_hi_i32 s6, s30, 0x7e07e07f
	s_lshr_b32 s7, s6, 31
	s_ashr_i32 s6, s6, 14
	s_add_i32 s14, s6, s7
	s_mul_i32 s6, s14, 0xffff7e00
	s_add_i32 s18, s30, s6
	s_cmpk_gt_i32 s18, 0x2fff
	s_mov_b64 s[6:7], -1
	s_cbranch_scc0 .LBB0_549
	s_cmpk_gt_u32 s18, 0x37ff
	s_cbranch_scc0 .LBB0_546
	s_cmpk_gt_u32 s18, 0x3fff
	s_cbranch_scc0 .LBB0_543
	s_cmpk_gt_u32 s18, 0x6bff
	s_mul_hi_i32 s15, s14, 0x2c00000
	s_mul_i32 s19, s14, 0x2c00000
	s_cbranch_scc0 .LBB0_476
	s_mov_b32 s7, s75
	v_readlane_b32 s72, v254, 45
	s_add_i32 s6, s18, 0x9400
	v_readlane_b32 s74, v254, 47
	v_readlane_b32 s75, v254, 48
	s_add_u32 s20, s74, s19
	s_addc_u32 s21, s75, s15
	s_mov_b32 s75, s7
	s_mul_i32 s7, s14, 0x1600000
	s_mul_hi_i32 s16, s14, 0x1600000
	s_add_u32 s7, s1, s7
	s_addc_u32 s16, s2, s16
	s_and_b32 s17, s6, 0xffc0
	s_and_b32 s6, s28, 0x7e0
	s_lshl_b32 s31, s6, 2
	s_add_u32 s20, s20, s31
	v_or_b32_e32 v2, s17, v66
	s_addc_u32 s21, s21, 0
	v_lshlrev_b32_e32 v64, 2, v68
	v_lshl_add_u64 v[0:1], s[20:21], 0, v[64:65]
	v_lshlrev_b32_e32 v64, 13, v2
	v_lshl_add_u64 v[0:1], v[0:1], 0, v[64:65]
	v_add_co_u32_e32 v2, vcc, s38, v0
	global_load_dword v4, v[0:1], off
	s_nop 0
	v_addc_co_u32_e32 v3, vcc, 0, v1, vcc
	global_load_dword v5, v[2:3], off
	v_add_co_u32_e32 v2, vcc, s40, v0
	s_mov_b32 s20, 0x5c000
	s_nop 0
	v_addc_co_u32_e32 v3, vcc, 0, v1, vcc
	global_load_dword v6, v[2:3], off
	v_add_co_u32_e32 v2, vcc, s42, v0
	s_lshl_b32 s17, s17, 1
	s_nop 0
	v_addc_co_u32_e32 v3, vcc, 0, v1, vcc
	global_load_dword v7, v[2:3], off
	v_add_co_u32_e32 v2, vcc, s36, v0
	v_lshlrev_b32_e32 v64, 1, v70
	s_nop 0
	v_addc_co_u32_e32 v3, vcc, 0, v1, vcc
	global_load_dword v8, v[2:3], off
	v_add_co_u32_e32 v2, vcc, s37, v0
	v_readlane_b32 s78, v254, 51
	s_nop 0
	v_addc_co_u32_e32 v3, vcc, 0, v1, vcc
	global_load_dword v9, v[2:3], off
	v_add_co_u32_e32 v2, vcc, s39, v0
	v_readlane_b32 s73, v254, 46
	s_nop 0
	v_addc_co_u32_e32 v3, vcc, 0, v1, vcc
	global_load_dword v10, v[2:3], off
	v_add_co_u32_e32 v2, vcc, s41, v0
	v_readlane_b32 s76, v254, 49
	s_nop 0
	v_addc_co_u32_e32 v3, vcc, 0, v1, vcc
	global_load_dword v11, v[2:3], off
	v_add_co_u32_e32 v2, vcc, s46, v0
	v_readlane_b32 s77, v254, 50
	s_nop 0
	v_addc_co_u32_e32 v3, vcc, 0, v1, vcc
	global_load_dword v12, v[2:3], off
	v_add_co_u32_e32 v2, vcc, s47, v0
	v_readlane_b32 s79, v254, 52
	s_nop 0
	v_addc_co_u32_e32 v3, vcc, 0, v1, vcc
	global_load_dword v13, v[2:3], off
	v_add_co_u32_e32 v2, vcc, s48, v0
	s_movk_i32 s78, 0x2000
	s_nop 0
	v_addc_co_u32_e32 v3, vcc, 0, v1, vcc
	global_load_dword v14, v[2:3], off
	v_add_co_u32_e32 v2, vcc, s49, v0
	s_nop 1
	v_addc_co_u32_e32 v3, vcc, 0, v1, vcc
	global_load_dword v15, v[2:3], off
	v_add_co_u32_e32 v2, vcc, s43, v0
	s_nop 1
	v_addc_co_u32_e32 v3, vcc, 0, v1, vcc
	global_load_dword v16, v[2:3], off
	v_add_co_u32_e32 v2, vcc, s50, v0
	s_nop 1
	v_addc_co_u32_e32 v3, vcc, 0, v1, vcc
	global_load_dword v17, v[2:3], off
	v_add_co_u32_e32 v2, vcc, s51, v0
	s_nop 1
	v_addc_co_u32_e32 v3, vcc, 0, v1, vcc
	global_load_dword v18, v[2:3], off
	v_add_co_u32_e32 v2, vcc, s52, v0
	s_nop 1
	v_addc_co_u32_e32 v3, vcc, 0, v1, vcc
	global_load_dword v19, v[2:3], off
	v_add_co_u32_e32 v2, vcc, s53, v0
	s_nop 1
	v_addc_co_u32_e32 v3, vcc, 0, v1, vcc
	global_load_dword v20, v[2:3], off
	v_add_co_u32_e32 v2, vcc, s54, v0
	s_nop 1
	v_addc_co_u32_e32 v3, vcc, 0, v1, vcc
	global_load_dword v21, v[2:3], off
	v_add_co_u32_e32 v2, vcc, s55, v0
	s_nop 1
	v_addc_co_u32_e32 v3, vcc, 0, v1, vcc
	global_load_dword v22, v[2:3], off
	v_add_co_u32_e32 v2, vcc, s62, v0
	s_nop 1
	v_addc_co_u32_e32 v3, vcc, 0, v1, vcc
	global_load_dword v23, v[2:3], off
	v_add_co_u32_e32 v2, vcc, s63, v0
	s_nop 1
	v_addc_co_u32_e32 v3, vcc, 0, v1, vcc
	global_load_dword v24, v[2:3], off
	v_add_co_u32_e32 v2, vcc, s64, v0
	s_nop 1
	v_addc_co_u32_e32 v3, vcc, 0, v1, vcc
	global_load_dword v25, v[2:3], off
	v_add_co_u32_e32 v2, vcc, s65, v0
	s_nop 1
	v_addc_co_u32_e32 v3, vcc, 0, v1, vcc
	global_load_dword v26, v[2:3], off
	v_add_co_u32_e32 v2, vcc, s20, v0
	s_mov_b32 s20, 0x64000
	s_nop 0
	v_addc_co_u32_e32 v3, vcc, 0, v1, vcc
	global_load_dword v27, v[2:3], off
	v_add_co_u32_e32 v2, vcc, s44, v0
	s_nop 1
	v_addc_co_u32_e32 v3, vcc, 0, v1, vcc
	global_load_dword v28, v[2:3], off
	v_add_co_u32_e32 v2, vcc, s20, v0
	s_mov_b32 s20, 0x68000
	s_nop 0
	v_addc_co_u32_e32 v3, vcc, 0, v1, vcc
	global_load_dword v29, v[2:3], off
	v_add_co_u32_e32 v2, vcc, s20, v0
	s_mov_b32 s20, 0x6c000
	s_nop 0
	v_addc_co_u32_e32 v3, vcc, 0, v1, vcc
	global_load_dword v30, v[2:3], off
	v_add_co_u32_e32 v2, vcc, s20, v0
	s_mov_b32 s20, 0x70000
	s_nop 0
	v_addc_co_u32_e32 v3, vcc, 0, v1, vcc
	global_load_dword v31, v[2:3], off
	v_add_co_u32_e32 v2, vcc, s20, v0
	s_mov_b32 s20, 0x74000
	s_nop 0
	v_addc_co_u32_e32 v3, vcc, 0, v1, vcc
	global_load_dword v32, v[2:3], off
	v_add_co_u32_e32 v2, vcc, s20, v0
	s_mov_b32 s20, 0x78000
	s_nop 0
	v_addc_co_u32_e32 v3, vcc, 0, v1, vcc
	global_load_dword v33, v[2:3], off
	v_add_co_u32_e32 v2, vcc, s20, v0
	s_mov_b32 s20, 0x7c000
	s_nop 0
	v_addc_co_u32_e32 v3, vcc, 0, v1, vcc
	v_add_co_u32_e32 v0, vcc, s20, v0
	global_load_dword v2, v[2:3], off
	s_nop 0
	v_addc_co_u32_e32 v1, vcc, 0, v1, vcc
	global_load_dword v0, v[0:1], off
	v_add_u32_e32 v1, 0x400, v71
	s_waitcnt vmcnt(0)
	s_cselect_b32 s32, 1, 0
	s_add_i32 s88, s30, s0
	s_cmp_gt_i32 s88, 0x103ff
	s_cbranch_scc1 .Ltp_end_p0
	s_cmp_ge_u32 s88, 0x8200
	s_cselect_b32 s92, 1, 0
	s_cselect_b32 s81, 0x8200, 0
	s_sub_i32 s88, s88, s81
	s_cmp_lt_u32 s88, 0x3000
	s_cbranch_scc0 .Ltp_b_p0
	s_mul_i32 s81, s92, 0x6000000
	s_add_u32 s84, s60, s81
	s_addc_u32 s85, s61, 0
	s_lshr_b32 s81, s88, 7
	s_mul_i32 s81, s81, 0xaaab
	s_lshr_b32 s81, s81, 17
	s_mul_i32 s90, s81, 0x180
	s_sub_i32 s88, s88, s90
	s_mov_b32 s90, 0xc000
	s_branch .Ltp_go_p0

.Ltp_end_p0:
	s_cmp_lg_u32 s32, 0
	ds_write2_b32 v71, v4, v5 offset1:66
	ds_write2_b32 v71, v6, v7 offset0:132 offset1:198
	ds_write2_b32 v1, v8, v9 offset0:8 offset1:74
	ds_write2_b32 v1, v10, v11 offset0:140 offset1:206
	v_add_u32_e32 v1, 0x800, v71
	ds_write2_b32 v1, v12, v13 offset0:16 offset1:82
	ds_write2_b32 v1, v14, v15 offset0:148 offset1:214
	v_add_u32_e32 v1, 0xc00, v71
	ds_write2_b32 v1, v16, v17 offset0:24 offset1:90
	ds_write2_b32 v1, v18, v19 offset0:156 offset1:222
	v_add_u32_e32 v1, 0x1000, v71
	ds_write2_b32 v1, v20, v21 offset0:32 offset1:98
	ds_write2_b32 v1, v22, v23 offset0:164 offset1:230
	v_add_u32_e32 v1, 0x1400, v71
	ds_write2_b32 v1, v24, v25 offset0:40 offset1:106
	ds_write2_b32 v1, v26, v27 offset0:172 offset1:238
	v_add_u32_e32 v1, 0x1800, v71
	ds_write2_b32 v1, v28, v29 offset0:48 offset1:114
	ds_write2_b32 v1, v30, v31 offset0:180 offset1:246
	v_add_u32_e32 v1, 0x1c00, v71
	ds_write2_b32 v1, v32, v33 offset0:56 offset1:122
	ds_write2_b32 v1, v2, v0 offset0:188 offset1:254
	s_waitcnt lgkmcnt(0)
	ds_read2_b32 v[6:7], v73 offset0:33 offset1:41
	ds_read2_b32 v[8:9], v73 offset1:8
	ds_read2_b32 v[10:11], v73 offset0:66 offset1:74
	ds_read2_b32 v[12:13], v73 offset0:99 offset1:107
	ds_read2_b32 v[14:15], v73 offset0:132 offset1:140
	ds_read2_b32 v[16:17], v73 offset0:165 offset1:173
	ds_read2_b32 v[18:19], v73 offset0:198 offset1:206
	ds_read2_b32 v[20:21], v73 offset0:231 offset1:239
	s_add_u32 s20, s7, s17
	s_waitcnt lgkmcnt(6)
	v_cvt_pk_bf16_f32 v0, v8, v6
	v_or_b32_e32 v6, s6, v72
	s_addc_u32 s21, s16, 0
	v_mul_u32_u24_e32 v6, 0x1600, v6
	v_lshl_add_u64 v[4:5], s[20:21], 0, v[64:65]
	v_lshlrev_b32_e32 v64, 1, v6
	v_or_b32_e32 v6, s6, v74
	v_mul_u32_u24_e32 v6, 0x1600, v6
	s_waitcnt lgkmcnt(4)
	v_cvt_pk_bf16_f32 v1, v10, v12
	s_waitcnt lgkmcnt(2)
	v_cvt_pk_bf16_f32 v2, v14, v16
	s_waitcnt lgkmcnt(0)
	v_cvt_pk_bf16_f32 v3, v18, v20
	v_lshl_add_u64 v[22:23], v[4:5], 0, v[64:65]
	v_lshlrev_b32_e32 v64, 1, v6
	global_store_dwordx4 v[22:23], v[0:3], off
	s_nop 1
	v_cvt_pk_bf16_f32 v0, v9, v7
	v_cvt_pk_bf16_f32 v1, v11, v13
	v_cvt_pk_bf16_f32 v2, v15, v17
	v_cvt_pk_bf16_f32 v3, v19, v21
	v_lshl_add_u64 v[6:7], v[4:5], 0, v[64:65]
	global_store_dwordx4 v[6:7], v[0:3], off
	ds_read2_b32 v[6:7], v73 offset0:16 offset1:24
	ds_read2_b32 v[8:9], v73 offset0:49 offset1:57
	ds_read2_b32 v[10:11], v73 offset0:82 offset1:90
	ds_read2_b32 v[12:13], v73 offset0:115 offset1:123
	ds_read2_b32 v[14:15], v73 offset0:148 offset1:156
	ds_read2_b32 v[16:17], v73 offset0:181 offset1:189
	ds_read2_b32 v[18:19], v73 offset0:214 offset1:222
	ds_read2_b32 v[20:21], v73 offset0:247 offset1:255
	s_waitcnt lgkmcnt(6)
	v_cvt_pk_bf16_f32 v0, v6, v8
	v_or_b32_e32 v6, s6, v75
	v_mul_u32_u24_e32 v6, 0x1600, v6
	v_lshlrev_b32_e32 v64, 1, v6
	v_or_b32_e32 v6, s6, v76
	v_mul_u32_u24_e32 v6, 0x1600, v6
	s_waitcnt lgkmcnt(4)
	v_cvt_pk_bf16_f32 v1, v10, v12
	s_waitcnt lgkmcnt(2)
	v_cvt_pk_bf16_f32 v2, v14, v16
	s_waitcnt lgkmcnt(0)
	v_cvt_pk_bf16_f32 v3, v18, v20
	v_lshl_add_u64 v[22:23], v[4:5], 0, v[64:65]
	v_lshlrev_b32_e32 v64, 1, v6
	global_store_dwordx4 v[22:23], v[0:3], off
	v_lshl_add_u64 v[4:5], v[4:5], 0, v[64:65]
	s_mov_b64 s[6:7], 0
	v_cvt_pk_bf16_f32 v0, v7, v9
	v_cvt_pk_bf16_f32 v1, v11, v13
	v_cvt_pk_bf16_f32 v2, v15, v17
	v_cvt_pk_bf16_f32 v3, v19, v21
	global_store_dwordx4 v[4:5], v[0:3], off
	s_waitcnt lgkmcnt(0)

.Ltp_end_gu:
	s_cmp_lg_u32 s32, 0
	s_add_u32 s6, s5, s19
	s_addc_u32 s7, s9, s15
	s_lshl_b32 s15, s31, 1
	s_add_u32 s6, s6, s15
	s_addc_u32 s7, s7, 0
	v_lshlrev_b32_e32 v64, 1, v70
	v_lshl_add_u64 v[4:5], s[6:7], 0, v[64:65]
	s_and_b32 s6, 0xffff, s21
	s_cmpk_gt_u32 s6, 0xaf
	s_cselect_b32 s6, 0xffffea00, 0
	s_cselect_b32 s7, 0x80, 0
	s_add_i32 s6, s6, s20
	ds_write_b32 v1, v31 offset:4488
	s_lshl_b32 s6, s6, 1
	s_waitcnt lgkmcnt(0)
	s_and_b32 s6, s6, 0xffffff00
	s_and_b32 s15, s20, 0x60
	ds_read2_b32 v[6:7], v73 offset0:33 offset1:41
	ds_read2_b32 v[8:9], v73 offset1:8
	ds_read2_b32 v[10:11], v73 offset0:66 offset1:74
	ds_read2_b32 v[12:13], v73 offset0:99 offset1:107
	ds_read2_b32 v[14:15], v73 offset0:132 offset1:140
	ds_read2_b32 v[16:17], v73 offset0:165 offset1:173
	ds_read2_b32 v[18:19], v73 offset0:198 offset1:206
	ds_read2_b32 v[20:21], v73 offset0:231 offset1:239
	s_or_b32 s6, s6, s15
	s_or_b32 s6, s6, s7
	v_or_b32_e32 v22, s6, v72
	v_ashrrev_i32_e32 v23, 31, v22
	v_lshlrev_b64 v[22:23], 12, v[22:23]
	s_waitcnt lgkmcnt(6)
	v_cvt_pk_bf16_f32 v0, v8, v6
	s_waitcnt lgkmcnt(4)
	v_cvt_pk_bf16_f32 v1, v10, v12
	s_waitcnt lgkmcnt(2)
	v_cvt_pk_bf16_f32 v2, v14, v16
	s_waitcnt lgkmcnt(0)
	v_cvt_pk_bf16_f32 v3, v18, v20
	v_lshl_add_u64 v[22:23], v[4:5], 0, v[22:23]
	v_or_b32_e32 v6, s6, v74
	global_store_dwordx4 v[22:23], v[0:3], off
	v_or_b32_e32 v22, s6, v75
	v_ashrrev_i32_e32 v23, 31, v22
	v_cvt_pk_bf16_f32 v0, v9, v7
	v_ashrrev_i32_e32 v7, 31, v6
	v_lshlrev_b64 v[6:7], 12, v[6:7]
	v_cvt_pk_bf16_f32 v1, v11, v13
	v_cvt_pk_bf16_f32 v2, v15, v17
	v_cvt_pk_bf16_f32 v3, v19, v21
	v_lshl_add_u64 v[6:7], v[4:5], 0, v[6:7]
	global_store_dwordx4 v[6:7], v[0:3], off
	ds_read2_b32 v[6:7], v73 offset0:49 offset1:57
	ds_read2_b32 v[8:9], v73 offset0:16 offset1:24
	ds_read2_b32 v[10:11], v73 offset0:82 offset1:90
	ds_read2_b32 v[12:13], v73 offset0:115 offset1:123
	ds_read2_b32 v[14:15], v73 offset0:148 offset1:156
	ds_read2_b32 v[16:17], v73 offset0:181 offset1:189
	ds_read2_b32 v[18:19], v73 offset0:214 offset1:222
	ds_read2_b32 v[20:21], v73 offset0:247 offset1:255
	v_lshlrev_b64 v[22:23], 12, v[22:23]
	s_waitcnt lgkmcnt(6)
	v_cvt_pk_bf16_f32 v0, v8, v6
	s_waitcnt lgkmcnt(4)
	v_cvt_pk_bf16_f32 v1, v10, v12
	s_waitcnt lgkmcnt(2)
	v_cvt_pk_bf16_f32 v2, v14, v16
	s_waitcnt lgkmcnt(0)
	v_cvt_pk_bf16_f32 v3, v18, v20
	v_lshl_add_u64 v[22:23], v[4:5], 0, v[22:23]
	v_or_b32_e32 v6, s6, v76
	global_store_dwordx4 v[22:23], v[0:3], off
	s_nop 1
	v_cvt_pk_bf16_f32 v0, v9, v7
	v_ashrrev_i32_e32 v7, 31, v6
	v_lshlrev_b64 v[6:7], 12, v[6:7]
	v_cvt_pk_bf16_f32 v1, v11, v13
	v_cvt_pk_bf16_f32 v2, v15, v17
	v_cvt_pk_bf16_f32 v3, v19, v21
	v_lshl_add_u64 v[4:5], v[4:5], 0, v[6:7]
	global_store_dwordx4 v[4:5], v[0:3], off
	s_waitcnt lgkmcnt(0)

.LBB0_543:
	s_andn2_b64 vcc, exec, s[6:7]
	s_cbranch_vccnz .LBB0_545
	s_ashr_i32 s15, s14, 31
	s_add_i32 s19, s18, 0xc800
	s_lshl_b64 s[6:7], s[14:15], 24
	s_add_u32 s20, s68, s6
	s_addc_u32 s21, s69, s7
	s_lshl_b64 s[16:17], s[14:15], 23
	s_add_u32 s7, s22, s16
	s_addc_u32 s15, s23, s17
	s_and_b32 s6, s28, 0x7e0
	s_and_b32 s16, s19, 0xffc0
	s_lshl_b32 s17, s6, 2
	s_add_u32 s20, s20, s17
	v_or_b32_e32 v2, s16, v66
	s_addc_u32 s21, s21, 0
	v_lshlrev_b32_e32 v64, 2, v68
	v_lshl_add_u64 v[0:1], s[20:21], 0, v[64:65]
	v_lshlrev_b32_e32 v64, 13, v2
	v_lshl_add_u64 v[0:1], v[0:1], 0, v[64:65]
	v_add_co_u32_e32 v2, vcc, s38, v0
	global_load_dword v4, v[0:1], off
	s_nop 0
	v_addc_co_u32_e32 v3, vcc, 0, v1, vcc
	global_load_dword v5, v[2:3], off
	v_add_co_u32_e32 v2, vcc, s40, v0
	s_mov_b32 s17, 0x5c000
	s_nop 0
	v_addc_co_u32_e32 v3, vcc, 0, v1, vcc
	global_load_dword v6, v[2:3], off
	v_add_co_u32_e32 v2, vcc, s42, v0
	s_lshl_b32 s16, s16, 1
	s_nop 0
	v_addc_co_u32_e32 v3, vcc, 0, v1, vcc
	global_load_dword v7, v[2:3], off
	v_add_co_u32_e32 v2, vcc, s36, v0
	s_add_u32 s16, s7, s16
	s_nop 0
	v_addc_co_u32_e32 v3, vcc, 0, v1, vcc
	global_load_dword v8, v[2:3], off
	v_add_co_u32_e32 v2, vcc, s37, v0
	v_lshlrev_b32_e32 v64, 1, v70
	s_nop 0
	v_addc_co_u32_e32 v3, vcc, 0, v1, vcc
	global_load_dword v9, v[2:3], off
	v_add_co_u32_e32 v2, vcc, s39, v0
	s_nop 1
	v_addc_co_u32_e32 v3, vcc, 0, v1, vcc
	global_load_dword v10, v[2:3], off
	v_add_co_u32_e32 v2, vcc, s41, v0
	s_nop 1
	v_addc_co_u32_e32 v3, vcc, 0, v1, vcc
	global_load_dword v11, v[2:3], off
	v_add_co_u32_e32 v2, vcc, s46, v0
	s_nop 1
	v_addc_co_u32_e32 v3, vcc, 0, v1, vcc
	global_load_dword v12, v[2:3], off
	v_add_co_u32_e32 v2, vcc, s47, v0
	s_nop 1
	v_addc_co_u32_e32 v3, vcc, 0, v1, vcc
	global_load_dword v13, v[2:3], off
	v_add_co_u32_e32 v2, vcc, s48, v0
	s_nop 1
	v_addc_co_u32_e32 v3, vcc, 0, v1, vcc
	global_load_dword v14, v[2:3], off
	v_add_co_u32_e32 v2, vcc, s49, v0
	s_nop 1
	v_addc_co_u32_e32 v3, vcc, 0, v1, vcc
	global_load_dword v15, v[2:3], off
	v_add_co_u32_e32 v2, vcc, s43, v0
	s_nop 1
	v_addc_co_u32_e32 v3, vcc, 0, v1, vcc
	global_load_dword v16, v[2:3], off
	v_add_co_u32_e32 v2, vcc, s50, v0
	s_nop 1
	v_addc_co_u32_e32 v3, vcc, 0, v1, vcc
	global_load_dword v17, v[2:3], off
	v_add_co_u32_e32 v2, vcc, s51, v0
	s_nop 1
	v_addc_co_u32_e32 v3, vcc, 0, v1, vcc
	global_load_dword v18, v[2:3], off
	v_add_co_u32_e32 v2, vcc, s52, v0
	s_nop 1
	v_addc_co_u32_e32 v3, vcc, 0, v1, vcc
	global_load_dword v19, v[2:3], off
	v_add_co_u32_e32 v2, vcc, s53, v0
	s_nop 1
	v_addc_co_u32_e32 v3, vcc, 0, v1, vcc
	global_load_dword v20, v[2:3], off
	v_add_co_u32_e32 v2, vcc, s54, v0
	s_nop 1
	v_addc_co_u32_e32 v3, vcc, 0, v1, vcc
	global_load_dword v21, v[2:3], off
	v_add_co_u32_e32 v2, vcc, s55, v0
	s_nop 1
	v_addc_co_u32_e32 v3, vcc, 0, v1, vcc
	global_load_dword v22, v[2:3], off
	v_add_co_u32_e32 v2, vcc, s62, v0
	s_nop 1
	v_addc_co_u32_e32 v3, vcc, 0, v1, vcc
	global_load_dword v23, v[2:3], off
	v_add_co_u32_e32 v2, vcc, s63, v0
	s_nop 1
	v_addc_co_u32_e32 v3, vcc, 0, v1, vcc
	global_load_dword v24, v[2:3], off
	v_add_co_u32_e32 v2, vcc, s64, v0
	s_nop 1
	v_addc_co_u32_e32 v3, vcc, 0, v1, vcc
	global_load_dword v25, v[2:3], off
	v_add_co_u32_e32 v2, vcc, s65, v0
	s_nop 1
	v_addc_co_u32_e32 v3, vcc, 0, v1, vcc
	global_load_dword v26, v[2:3], off
	v_add_co_u32_e32 v2, vcc, s17, v0
	s_mov_b32 s17, 0x64000
	s_nop 0
	v_addc_co_u32_e32 v3, vcc, 0, v1, vcc
	global_load_dword v27, v[2:3], off
	v_add_co_u32_e32 v2, vcc, s44, v0
	s_nop 1
	v_addc_co_u32_e32 v3, vcc, 0, v1, vcc
	global_load_dword v28, v[2:3], off
	v_add_co_u32_e32 v2, vcc, s17, v0
	s_mov_b32 s17, 0x68000
	s_nop 0
	v_addc_co_u32_e32 v3, vcc, 0, v1, vcc
	global_load_dword v29, v[2:3], off
	v_add_co_u32_e32 v2, vcc, s17, v0
	s_mov_b32 s17, 0x6c000
	s_nop 0
	v_addc_co_u32_e32 v3, vcc, 0, v1, vcc
	global_load_dword v30, v[2:3], off
	v_add_co_u32_e32 v2, vcc, s17, v0
	s_mov_b32 s17, 0x70000
	s_nop 0
	v_addc_co_u32_e32 v3, vcc, 0, v1, vcc
	global_load_dword v31, v[2:3], off
	v_add_co_u32_e32 v2, vcc, s17, v0
	s_mov_b32 s17, 0x74000
	s_nop 0
	v_addc_co_u32_e32 v3, vcc, 0, v1, vcc
	global_load_dword v32, v[2:3], off
	v_add_co_u32_e32 v2, vcc, s17, v0
	s_mov_b32 s17, 0x78000
	s_nop 0
	v_addc_co_u32_e32 v3, vcc, 0, v1, vcc
	global_load_dword v33, v[2:3], off
	v_add_co_u32_e32 v2, vcc, s17, v0
	s_mov_b32 s17, 0x7c000
	s_nop 0
	v_addc_co_u32_e32 v3, vcc, 0, v1, vcc
	v_add_co_u32_e32 v0, vcc, s17, v0
	global_load_dword v2, v[2:3], off
	s_nop 0
	v_addc_co_u32_e32 v1, vcc, 0, v1, vcc
	global_load_dword v0, v[0:1], off
	v_add_u32_e32 v1, 0x400, v71
	s_waitcnt vmcnt(0)
	s_cselect_b32 s32, 1, 0
	s_add_i32 s88, s30, s0
	s_cmp_gt_i32 s88, 0x103ff
	s_cbranch_scc1 .Ltp_end_p1
	s_cmp_ge_u32 s88, 0x8200
	s_cselect_b32 s92, 1, 0
	s_cselect_b32 s81, 0x8200, 0
	s_sub_i32 s88, s88, s81
	s_cmp_lt_u32 s88, 0x3000
	s_cbranch_scc0 .Ltp_b_p1
	s_mul_i32 s81, s92, 0x6000000
	s_add_u32 s84, s60, s81
	s_addc_u32 s85, s61, 0
	s_lshr_b32 s81, s88, 7
	s_mul_i32 s81, s81, 0xaaab
	s_lshr_b32 s81, s81, 17
	s_mul_i32 s90, s81, 0x180
	s_sub_i32 s88, s88, s90
	s_mov_b32 s90, 0xc000
	s_branch .Ltp_go_p1

.Ltp_end_p1:
	s_cmp_lg_u32 s32, 0
	ds_write2_b32 v71, v4, v5 offset1:66
	ds_write2_b32 v71, v6, v7 offset0:132 offset1:198
	ds_write2_b32 v1, v8, v9 offset0:8 offset1:74
	ds_write2_b32 v1, v10, v11 offset0:140 offset1:206
	v_add_u32_e32 v1, 0x800, v71
	ds_write2_b32 v1, v12, v13 offset0:16 offset1:82
	ds_write2_b32 v1, v14, v15 offset0:148 offset1:214
	v_add_u32_e32 v1, 0xc00, v71
	ds_write2_b32 v1, v16, v17 offset0:24 offset1:90
	ds_write2_b32 v1, v18, v19 offset0:156 offset1:222
	v_add_u32_e32 v1, 0x1000, v71
	ds_write2_b32 v1, v20, v21 offset0:32 offset1:98
	ds_write2_b32 v1, v22, v23 offset0:164 offset1:230
	v_add_u32_e32 v1, 0x1400, v71
	ds_write2_b32 v1, v24, v25 offset0:40 offset1:106
	ds_write2_b32 v1, v26, v27 offset0:172 offset1:238
	v_add_u32_e32 v1, 0x1800, v71
	ds_write2_b32 v1, v28, v29 offset0:48 offset1:114
	ds_write2_b32 v1, v30, v31 offset0:180 offset1:246
	v_add_u32_e32 v1, 0x1c00, v71
	ds_write2_b32 v1, v32, v33 offset0:56 offset1:122
	ds_write2_b32 v1, v2, v0 offset0:188 offset1:254
	s_waitcnt lgkmcnt(0)
	ds_read2_b32 v[6:7], v73 offset0:33 offset1:41
	ds_read2_b32 v[8:9], v73 offset1:8
	ds_read2_b32 v[10:11], v73 offset0:66 offset1:74
	ds_read2_b32 v[12:13], v73 offset0:99 offset1:107
	ds_read2_b32 v[14:15], v73 offset0:132 offset1:140
	ds_read2_b32 v[16:17], v73 offset0:165 offset1:173
	ds_read2_b32 v[18:19], v73 offset0:198 offset1:206
	ds_read2_b32 v[20:21], v73 offset0:231 offset1:239
	s_addc_u32 s17, s15, 0
	s_waitcnt lgkmcnt(6)
	v_cvt_pk_bf16_f32 v0, v8, v6
	v_or_b32_e32 v6, s6, v72
	v_lshl_add_u64 v[4:5], s[16:17], 0, v[64:65]
	v_lshlrev_b32_e32 v64, 12, v6
	v_or_b32_e32 v6, s6, v74
	s_waitcnt lgkmcnt(4)
	v_cvt_pk_bf16_f32 v1, v10, v12
	s_waitcnt lgkmcnt(2)
	v_cvt_pk_bf16_f32 v2, v14, v16
	s_waitcnt lgkmcnt(0)
	v_cvt_pk_bf16_f32 v3, v18, v20
	v_lshl_add_u64 v[22:23], v[4:5], 0, v[64:65]
	v_lshlrev_b32_e32 v64, 12, v6
	global_store_dwordx4 v[22:23], v[0:3], off
	s_nop 1
	v_cvt_pk_bf16_f32 v0, v9, v7
	v_cvt_pk_bf16_f32 v1, v11, v13
	v_cvt_pk_bf16_f32 v2, v15, v17
	v_cvt_pk_bf16_f32 v3, v19, v21
	v_lshl_add_u64 v[6:7], v[4:5], 0, v[64:65]
	global_store_dwordx4 v[6:7], v[0:3], off
	ds_read2_b32 v[6:7], v73 offset0:49 offset1:57
	ds_read2_b32 v[8:9], v73 offset0:16 offset1:24
	ds_read2_b32 v[10:11], v73 offset0:82 offset1:90
	ds_read2_b32 v[12:13], v73 offset0:115 offset1:123
	ds_read2_b32 v[14:15], v73 offset0:148 offset1:156
	ds_read2_b32 v[16:17], v73 offset0:181 offset1:189
	ds_read2_b32 v[18:19], v73 offset0:214 offset1:222
	ds_read2_b32 v[20:21], v73 offset0:247 offset1:255
	s_waitcnt lgkmcnt(6)
	v_cvt_pk_bf16_f32 v0, v8, v6
	v_or_b32_e32 v6, s6, v75
	v_lshlrev_b32_e32 v64, 12, v6
	v_or_b32_e32 v6, s6, v76
	s_waitcnt lgkmcnt(4)
	v_cvt_pk_bf16_f32 v1, v10, v12
	s_waitcnt lgkmcnt(2)
	v_cvt_pk_bf16_f32 v2, v14, v16
	s_waitcnt lgkmcnt(0)
	v_cvt_pk_bf16_f32 v3, v18, v20
	v_lshl_add_u64 v[22:23], v[4:5], 0, v[64:65]
	v_lshlrev_b32_e32 v64, 12, v6
	global_store_dwordx4 v[22:23], v[0:3], off
	v_lshl_add_u64 v[4:5], v[4:5], 0, v[64:65]
	s_nop 0
	v_cvt_pk_bf16_f32 v0, v9, v7
	v_cvt_pk_bf16_f32 v1, v11, v13
	v_cvt_pk_bf16_f32 v2, v15, v17
	v_cvt_pk_bf16_f32 v3, v19, v21
	global_store_dwordx4 v[4:5], v[0:3], off
	s_waitcnt lgkmcnt(0)

.LBB0_546:
	s_andn2_b64 vcc, exec, s[6:7]
	s_cbranch_vccnz .LBB0_548
	s_ashr_i32 s15, s14, 31
	s_add_i32 s19, s18, 0xd000
	s_lshl_b64 s[6:7], s[14:15], 24
	s_add_u32 s20, s66, s6
	s_addc_u32 s21, s67, s7
	s_lshl_b64 s[16:17], s[14:15], 23
	s_add_u32 s7, s24, s16
	s_addc_u32 s15, s25, s17
	s_and_b32 s6, s28, 0x7e0
	s_and_b32 s16, s19, 0xffc0
	s_lshl_b32 s17, s6, 2
	s_add_u32 s20, s20, s17
	v_or_b32_e32 v2, s16, v66
	s_addc_u32 s21, s21, 0
	v_lshlrev_b32_e32 v64, 2, v68
	v_lshl_add_u64 v[0:1], s[20:21], 0, v[64:65]
	v_lshlrev_b32_e32 v64, 13, v2
	v_lshl_add_u64 v[0:1], v[0:1], 0, v[64:65]
	v_add_co_u32_e32 v2, vcc, s38, v0
	global_load_dword v4, v[0:1], off
	s_nop 0
	v_addc_co_u32_e32 v3, vcc, 0, v1, vcc
	global_load_dword v5, v[2:3], off
	v_add_co_u32_e32 v2, vcc, s40, v0
	s_mov_b32 s17, 0x5c000
	s_nop 0
	v_addc_co_u32_e32 v3, vcc, 0, v1, vcc
	global_load_dword v6, v[2:3], off
	v_add_co_u32_e32 v2, vcc, s42, v0
	s_lshl_b32 s16, s16, 1
	s_nop 0
	v_addc_co_u32_e32 v3, vcc, 0, v1, vcc
	global_load_dword v7, v[2:3], off
	v_add_co_u32_e32 v2, vcc, s36, v0
	s_add_u32 s16, s7, s16
	s_nop 0
	v_addc_co_u32_e32 v3, vcc, 0, v1, vcc
	global_load_dword v8, v[2:3], off
	v_add_co_u32_e32 v2, vcc, s37, v0
	v_lshlrev_b32_e32 v64, 1, v70
	s_nop 0
	v_addc_co_u32_e32 v3, vcc, 0, v1, vcc
	global_load_dword v9, v[2:3], off
	v_add_co_u32_e32 v2, vcc, s39, v0
	s_nop 1
	v_addc_co_u32_e32 v3, vcc, 0, v1, vcc
	global_load_dword v10, v[2:3], off
	v_add_co_u32_e32 v2, vcc, s41, v0
	s_nop 1
	v_addc_co_u32_e32 v3, vcc, 0, v1, vcc
	global_load_dword v11, v[2:3], off
	v_add_co_u32_e32 v2, vcc, s46, v0
	s_nop 1
	v_addc_co_u32_e32 v3, vcc, 0, v1, vcc
	global_load_dword v12, v[2:3], off
	v_add_co_u32_e32 v2, vcc, s47, v0
	s_nop 1
	v_addc_co_u32_e32 v3, vcc, 0, v1, vcc
	global_load_dword v13, v[2:3], off
	v_add_co_u32_e32 v2, vcc, s48, v0
	s_nop 1
	v_addc_co_u32_e32 v3, vcc, 0, v1, vcc
	global_load_dword v14, v[2:3], off
	v_add_co_u32_e32 v2, vcc, s49, v0
	s_nop 1
	v_addc_co_u32_e32 v3, vcc, 0, v1, vcc
	global_load_dword v15, v[2:3], off
	v_add_co_u32_e32 v2, vcc, s43, v0
	s_nop 1
	v_addc_co_u32_e32 v3, vcc, 0, v1, vcc
	global_load_dword v16, v[2:3], off
	v_add_co_u32_e32 v2, vcc, s50, v0
	s_nop 1
	v_addc_co_u32_e32 v3, vcc, 0, v1, vcc
	global_load_dword v17, v[2:3], off
	v_add_co_u32_e32 v2, vcc, s51, v0
	s_nop 1
	v_addc_co_u32_e32 v3, vcc, 0, v1, vcc
	global_load_dword v18, v[2:3], off
	v_add_co_u32_e32 v2, vcc, s52, v0
	s_nop 1
	v_addc_co_u32_e32 v3, vcc, 0, v1, vcc
	global_load_dword v19, v[2:3], off
	v_add_co_u32_e32 v2, vcc, s53, v0
	s_nop 1
	v_addc_co_u32_e32 v3, vcc, 0, v1, vcc
	global_load_dword v20, v[2:3], off
	v_add_co_u32_e32 v2, vcc, s54, v0
	s_nop 1
	v_addc_co_u32_e32 v3, vcc, 0, v1, vcc
	global_load_dword v21, v[2:3], off
	v_add_co_u32_e32 v2, vcc, s55, v0
	s_nop 1
	v_addc_co_u32_e32 v3, vcc, 0, v1, vcc
	global_load_dword v22, v[2:3], off
	v_add_co_u32_e32 v2, vcc, s62, v0
	s_nop 1
	v_addc_co_u32_e32 v3, vcc, 0, v1, vcc
	global_load_dword v23, v[2:3], off
	v_add_co_u32_e32 v2, vcc, s63, v0
	s_nop 1
	v_addc_co_u32_e32 v3, vcc, 0, v1, vcc
	global_load_dword v24, v[2:3], off
	v_add_co_u32_e32 v2, vcc, s64, v0
	s_nop 1
	v_addc_co_u32_e32 v3, vcc, 0, v1, vcc
	global_load_dword v25, v[2:3], off
	v_add_co_u32_e32 v2, vcc, s65, v0
	s_nop 1
	v_addc_co_u32_e32 v3, vcc, 0, v1, vcc
	global_load_dword v26, v[2:3], off
	v_add_co_u32_e32 v2, vcc, s17, v0
	s_mov_b32 s17, 0x64000
	s_nop 0
	v_addc_co_u32_e32 v3, vcc, 0, v1, vcc
	global_load_dword v27, v[2:3], off
	v_add_co_u32_e32 v2, vcc, s44, v0
	s_nop 1
	v_addc_co_u32_e32 v3, vcc, 0, v1, vcc
	global_load_dword v28, v[2:3], off
	v_add_co_u32_e32 v2, vcc, s17, v0
	s_mov_b32 s17, 0x68000
	s_nop 0
	v_addc_co_u32_e32 v3, vcc, 0, v1, vcc
	global_load_dword v29, v[2:3], off
	v_add_co_u32_e32 v2, vcc, s17, v0
	s_mov_b32 s17, 0x6c000
	s_nop 0
	v_addc_co_u32_e32 v3, vcc, 0, v1, vcc
	global_load_dword v30, v[2:3], off
	v_add_co_u32_e32 v2, vcc, s17, v0
	s_mov_b32 s17, 0x70000
	s_nop 0
	v_addc_co_u32_e32 v3, vcc, 0, v1, vcc
	global_load_dword v31, v[2:3], off
	v_add_co_u32_e32 v2, vcc, s17, v0
	s_mov_b32 s17, 0x74000
	s_nop 0
	v_addc_co_u32_e32 v3, vcc, 0, v1, vcc
	global_load_dword v32, v[2:3], off
	v_add_co_u32_e32 v2, vcc, s17, v0
	s_mov_b32 s17, 0x78000
	s_nop 0
	v_addc_co_u32_e32 v3, vcc, 0, v1, vcc
	global_load_dword v33, v[2:3], off
	v_add_co_u32_e32 v2, vcc, s17, v0
	s_mov_b32 s17, 0x7c000
	s_nop 0
	v_addc_co_u32_e32 v3, vcc, 0, v1, vcc
	v_add_co_u32_e32 v0, vcc, s17, v0
	global_load_dword v2, v[2:3], off
	s_nop 0
	v_addc_co_u32_e32 v1, vcc, 0, v1, vcc
	global_load_dword v0, v[0:1], off
	v_add_u32_e32 v1, 0x400, v71
	s_waitcnt vmcnt(0)
	s_cselect_b32 s32, 1, 0
	s_add_i32 s88, s30, s0
	s_cmp_gt_i32 s88, 0x103ff
	s_cbranch_scc1 .Ltp_end_p2
	s_cmp_ge_u32 s88, 0x8200
	s_cselect_b32 s92, 1, 0
	s_cselect_b32 s81, 0x8200, 0
	s_sub_i32 s88, s88, s81
	s_cmp_lt_u32 s88, 0x3000
	s_cbranch_scc0 .Ltp_b_p2
	s_mul_i32 s81, s92, 0x6000000
	s_add_u32 s84, s60, s81
	s_addc_u32 s85, s61, 0
	s_lshr_b32 s81, s88, 7
	s_mul_i32 s81, s81, 0xaaab
	s_lshr_b32 s81, s81, 17
	s_mul_i32 s90, s81, 0x180
	s_sub_i32 s88, s88, s90
	s_mov_b32 s90, 0xc000
	s_branch .Ltp_go_p2
